# M0 write hoisted ahead of the DMA address adds (drops the s_nop pads)
# baseline (speedup 1.0000x reference)
; template <int KB> __device__ __forceinline__ void qkt_half(f32x16& p, const char* K_lds, int r32, int hi, int kh, const char* qf, bf16x8 q0) {
;     p = f32x16{};
;     const char* kb[4];
; #pragma unroll
;     for (int dd = 0; dd < 4; ++dd) kb[dd] = K_lds + KB * SHM_K + kh * 8192 + KSWZ(r32, (dd * 16 + hi * 8) * 2);
; #pragma unroll
;     for (int d0 = 0; d0 < 8; ++d0) { const bf16x8 b0 = *reinterpret_cast<const bf16x8*>(kb[d0 & 3] + (d0 >> 2) * 128); const bf16x8 q = d0 == 0 ? q0 : *reinterpret_cast<const bf16x8*>(qf + (d0 - 1) * 1024); p = __builtin_amdgcn_mfma_f32_32x32x16_bf16(b0, q, p, 0, 0, 0); }
; }
.LBB0_369:
	s_waitcnt lgkmcnt(7)
	v_mfma_f32_32x32x16_bf16 v[128:143], v[96:99], v[144:147], 0
	s_waitcnt lgkmcnt(6)
	v_mfma_f32_32x32x16_bf16 v[128:143], v[68:71], v[148:151], v[128:143]
	s_add_i32 s90, s87, -3
	s_cmp_gt_u32 s90, s84
	s_cbranch_scc1 .Ld0_h1_noK
	s_add_i32 s90, s87, -2
	s_cmp_lg_u64 s[46:47], 0
	s_cselect_b32 s90, s90, s53
	s_lshl_b32 s90, s90, 14
	s_add_i32 m0, s100, 0x14000
	s_add_u32 s92, s98, s90
	s_addc_u32 s93, s99, 0
	global_load_lds_dwordx4 v250, s[92:93]
	s_add_i32 m0, s100, 0x16000
	s_add_u32 s92, s92, 0x2000
	s_addc_u32 s93, s93, 0
	global_load_lds_dwordx4 v250, s[92:93]
.Ld0_h1_noK:
	s_waitcnt lgkmcnt(5)
	v_mfma_f32_32x32x16_bf16 v[128:143], v[72:75], v[152:155], v[128:143]
	s_waitcnt lgkmcnt(4)
	v_mfma_f32_32x32x16_bf16 v[128:143], v[76:79], v[156:159], v[128:143]
	s_add_i32 s90, s87, -3
	s_add_i32 s91, s53, 1
	s_cmp_lg_u64 s[46:47], 0
	s_cselect_b32 s90, s90, s91
	s_lshl_b32 s90, s90, 14
	s_mov_b32 m0, s100
	s_add_u32 s92, s8, s90
	s_addc_u32 s93, s9, 0
	global_load_lds_dwordx4 v251, s[92:93]
	s_add_i32 m0, s100, 0x2000
	s_add_u32 s92, s92, 0x2000
	s_addc_u32 s93, s93, 0
	global_load_lds_dwordx4 v251, s[92:93]
	s_waitcnt lgkmcnt(3)
	v_mfma_f32_32x32x16_bf16 v[128:143], v[80:83], v[160:163], v[128:143]
	s_waitcnt lgkmcnt(2)
	v_mfma_f32_32x32x16_bf16 v[128:143], v[84:87], v[164:167], v[128:143]
	s_add_i32 m0, s100, 0x4000
	s_add_u32 s92, s12, s90
	s_addc_u32 s93, s13, 0
	global_load_lds_dwordx4 v251, s[92:93]
	s_add_i32 m0, s100, 0x6000
	s_add_u32 s92, s92, 0x2000
	s_addc_u32 s93, s93, 0
	global_load_lds_dwordx4 v251, s[92:93]
	s_waitcnt lgkmcnt(1)
	v_mfma_f32_32x32x16_bf16 v[128:143], v[88:91], v[168:171], v[128:143]
	s_waitcnt lgkmcnt(0)
	v_mfma_f32_32x32x16_bf16 v[128:143], v[92:95], v[252:255], v[128:143]
	s_mov_b64 s[4:5], -1
	s_and_b64 vcc, exec, s[48:49]
	s_cbranch_vccz .LBB0_371
	ds_read_b64_tr_b16 v[80:81], v194 offset:0xc000
	ds_read_b64_tr_b16 v[82:83], v194 offset:0xc800
	ds_read_b64_tr_b16 v[84:85], v194 offset:0xd000
	ds_read_b64_tr_b16 v[86:87], v194 offset:0xd800
	ds_read_b64_tr_b16 v[88:89], v194 offset:0xe000
	ds_read_b64_tr_b16 v[90:91], v194 offset:0xe800
	ds_read_b64_tr_b16 v[92:93], v194 offset:0xf000
	ds_read_b64_tr_b16 v[94:95], v194 offset:0xf800
	s_waitcnt lgkmcnt(0)
	s_nop 0
	v_mfma_f32_32x32x16_bf16 v[64:79], v[184:187], v[80:83], v[0:15]
	ds_read_b64_tr_b16 v[96:97], v194 offset:0xc200
	ds_read_b64_tr_b16 v[98:99], v194 offset:0xca00
	ds_read_b64_tr_b16 v[100:101], v194 offset:0xd200
	ds_read_b64_tr_b16 v[102:103], v194 offset:0xda00
	ds_read_b64_tr_b16 v[104:105], v194 offset:0xe200
	ds_read_b64_tr_b16 v[106:107], v194 offset:0xea00
	ds_read_b64_tr_b16 v[108:109], v194 offset:0xf200
	v_mfma_f32_32x32x16_bf16 v[64:79], v[180:183], v[84:87], v[64:79]
	ds_read_b64_tr_b16 v[110:111], v194 offset:0xfa00
	v_mfma_f32_32x32x16_bf16 v[64:79], v[172:175], v[88:91], v[64:79]
	v_mfma_f32_32x32x16_bf16 v[64:79], v[176:179], v[92:95], v[64:79]
	s_waitcnt lgkmcnt(0)
	v_mfma_f32_32x32x16_bf16 v[80:95], v[184:187], v[96:99], v[16:31]
	ds_read_b64_tr_b16 v[112:113], v194 offset:0xc400
	ds_read_b64_tr_b16 v[114:115], v194 offset:0xcc00
	ds_read_b64_tr_b16 v[116:117], v194 offset:0xd400
	ds_read_b64_tr_b16 v[118:119], v194 offset:0xdc00
	ds_read_b64_tr_b16 v[120:121], v194 offset:0xe400
	ds_read_b64_tr_b16 v[122:123], v194 offset:0xec00
	ds_read_b64_tr_b16 v[124:125], v194 offset:0xf400
	v_mfma_f32_32x32x16_bf16 v[80:95], v[180:183], v[100:103], v[80:95]
	ds_read_b64_tr_b16 v[126:127], v194 offset:0xfc00
	s_add_i32 s38, s87, -3
	s_add_i32 s50, s53, 1
	s_and_b64 s[4:5], s[46:47], exec
	s_cselect_b32 s4, s38, s50
	s_lshl_b32 s4, s4, 6
	s_cmp_le_i32 s4, s86
	s_cbranch_scc0 .Lm0_h1B_mk

; template <int KB> __device__ __forceinline__ void qkt_half(f32x16& p, const char* K_lds, int r32, int hi, int kh, const char* qf, bf16x8 q0) {
;     p = f32x16{};
;     const char* kb[4];
; #pragma unroll
;     for (int dd = 0; dd < 4; ++dd) kb[dd] = K_lds + KB * SHM_K + kh * 8192 + KSWZ(r32, (dd * 16 + hi * 8) * 2);
; #pragma unroll
;     for (int d0 = 0; d0 < 8; ++d0) { const bf16x8 b0 = *reinterpret_cast<const bf16x8*>(kb[d0 & 3] + (d0 >> 2) * 128); const bf16x8 q = d0 == 0 ? q0 : *reinterpret_cast<const bf16x8*>(qf + (d0 - 1) * 1024); p = __builtin_amdgcn_mfma_f32_32x32x16_bf16(b0, q, p, 0, 0, 0); }
; }
.LBB0_386:
	s_waitcnt lgkmcnt(7)
	v_mfma_f32_32x32x16_bf16 v[128:143], v[32:35], v[144:147], 0
	s_waitcnt lgkmcnt(6)
	v_mfma_f32_32x32x16_bf16 v[128:143], v[4:7], v[148:151], v[128:143]
	s_add_i32 s90, s87, -1
	s_cmp_gt_u32 s90, s85
	s_cbranch_scc1 .Ld0_h2_noK
	s_add_i32 s91, s53, -1
	s_cmp_lg_u64 s[46:47], 0
	s_cselect_b32 s90, s90, s91
	s_lshl_b32 s90, s90, 14
	s_add_i32 m0, s100, 0x10000
	s_add_u32 s92, s98, s90
	s_addc_u32 s93, s99, 0
	global_load_lds_dwordx4 v250, s[92:93]
	s_add_i32 m0, s100, 0x12000
	s_add_u32 s92, s92, 0x2000
	s_addc_u32 s93, s93, 0
	global_load_lds_dwordx4 v250, s[92:93]
.Ld0_h2_noK:
	s_waitcnt lgkmcnt(5)
	v_mfma_f32_32x32x16_bf16 v[128:143], v[8:11], v[152:155], v[128:143]
	s_waitcnt lgkmcnt(4)
	v_mfma_f32_32x32x16_bf16 v[128:143], v[12:15], v[156:159], v[128:143]
	s_add_i32 s90, s87, -2
	s_cmp_lg_u64 s[46:47], 0
	s_cselect_b32 s90, s90, s53
	s_lshl_b32 s90, s90, 14
	s_add_i32 m0, s100, 0x8000
	s_add_u32 s92, s8, s90
	s_addc_u32 s93, s9, 0
	global_load_lds_dwordx4 v251, s[92:93]
	s_add_i32 m0, s100, 0xa000
	s_add_u32 s92, s92, 0x2000
	s_addc_u32 s93, s93, 0
	global_load_lds_dwordx4 v251, s[92:93]
	s_waitcnt lgkmcnt(3)
	v_mfma_f32_32x32x16_bf16 v[128:143], v[16:19], v[160:163], v[128:143]
	s_waitcnt lgkmcnt(2)
	v_mfma_f32_32x32x16_bf16 v[128:143], v[20:23], v[164:167], v[128:143]
	s_add_i32 m0, s100, 0xc000
	s_add_u32 s92, s12, s90
	s_addc_u32 s93, s13, 0
	global_load_lds_dwordx4 v251, s[92:93]
	s_add_i32 m0, s100, 0xe000
	s_add_u32 s92, s92, 0x2000
	s_addc_u32 s93, s93, 0
	global_load_lds_dwordx4 v251, s[92:93]
	s_waitcnt lgkmcnt(1)
	v_mfma_f32_32x32x16_bf16 v[128:143], v[24:27], v[168:171], v[128:143]
	s_waitcnt lgkmcnt(0)
	v_mfma_f32_32x32x16_bf16 v[128:143], v[28:31], v[252:255], v[128:143]
	s_mov_b64 s[4:5], -1
	s_and_b64 vcc, exec, s[48:49]
	s_cbranch_vccz .LBB0_388
	ds_read_b64_tr_b16 v[16:17], v194 offset:0x4000
	ds_read_b64_tr_b16 v[18:19], v194 offset:0x4800
	ds_read_b64_tr_b16 v[20:21], v194 offset:0x5000
	ds_read_b64_tr_b16 v[22:23], v194 offset:0x5800
	ds_read_b64_tr_b16 v[24:25], v194 offset:0x6000
	ds_read_b64_tr_b16 v[26:27], v194 offset:0x6800
	ds_read_b64_tr_b16 v[28:29], v194 offset:0x7000
	ds_read_b64_tr_b16 v[30:31], v194 offset:0x7800
	s_waitcnt lgkmcnt(0)
	s_nop 0
	v_mfma_f32_32x32x16_bf16 v[0:15], v[184:187], v[16:19], v[64:79]
	ds_read_b64_tr_b16 v[32:33], v194 offset:0x4200
	ds_read_b64_tr_b16 v[34:35], v194 offset:0x4a00
	ds_read_b64_tr_b16 v[36:37], v194 offset:0x5200
	ds_read_b64_tr_b16 v[38:39], v194 offset:0x5a00
	ds_read_b64_tr_b16 v[40:41], v194 offset:0x6200
	ds_read_b64_tr_b16 v[42:43], v194 offset:0x6a00
	ds_read_b64_tr_b16 v[44:45], v194 offset:0x7200
	v_mfma_f32_32x32x16_bf16 v[0:15], v[180:183], v[20:23], v[0:15]
	ds_read_b64_tr_b16 v[46:47], v194 offset:0x7a00
	v_mfma_f32_32x32x16_bf16 v[0:15], v[172:175], v[24:27], v[0:15]
	v_mfma_f32_32x32x16_bf16 v[0:15], v[176:179], v[28:31], v[0:15]
	s_waitcnt lgkmcnt(0)
	v_mfma_f32_32x32x16_bf16 v[16:31], v[184:187], v[32:35], v[80:95]
	ds_read_b64_tr_b16 v[48:49], v194 offset:0x4400
	ds_read_b64_tr_b16 v[50:51], v194 offset:0x4c00
	ds_read_b64_tr_b16 v[52:53], v194 offset:0x5400
	ds_read_b64_tr_b16 v[54:55], v194 offset:0x5c00
	ds_read_b64_tr_b16 v[56:57], v194 offset:0x6400
	ds_read_b64_tr_b16 v[58:59], v194 offset:0x6c00
	ds_read_b64_tr_b16 v[60:61], v194 offset:0x7400
	v_mfma_f32_32x32x16_bf16 v[16:31], v[180:183], v[36:39], v[16:31]
	ds_read_b64_tr_b16 v[62:63], v194 offset:0x7c00
	s_and_b64 s[4:5], s[46:47], exec
	s_cselect_b32 s4, s89, s53
	s_lshl_b32 s4, s4, 6
	s_cmp_le_i32 s4, s86
	s_cbranch_scc0 .Lm0_h2B_mk
